# align64
# baseline (speedup 1.0000x reference)
; #define WAIT_V(n) asm volatile("s_waitcnt vmcnt(" #n ")" ::: "memory")
; #define BAR __builtin_amdgcn_s_barrier()
; template <int EPI>
; __device__ __forceinline__ void gemm_phase(const u16* __restrict__ A, const u16* __restrict__ Bt, const int K,
;                                            const int nN, char* shm, const EpiArgs& ea) {
;     ...
;     WAIT_V(0);
;     if (wr == 1) BAR;
;     BAR;
;     BAR;
;     for (int t = 0; t < nt - 2; t += 2) {
.LBB0_171:
	s_add_i32 s6, s66, 0x80
	s_lshr_b32 s67, s6, 7
	s_add_i32 s6, s7, 0x80
	s_lshr_b32 s70, s7, 7
	s_lshr_b32 s69, s66, 7
	s_lshr_b32 s68, s6, 7
	s_mul_i32 s68, s68, 0x84000
	s_mul_i32 s69, s69, 0x84000
	s_mul_i32 s70, s70, 0x84000
	s_mul_i32 s67, s67, 0x84000
	s_mov_b32 s71, -2
	s_mov_b32 s72, 0
	v_mov_b64_e32 v[0:1], 0
	v_mov_b64_e32 v[2:3], 0
	v_mov_b64_e32 v[4:5], 0
	v_mov_b64_e32 v[6:7], 0
	v_mov_b64_e32 v[8:9], 0
	v_mov_b64_e32 v[10:11], 0
	v_mov_b64_e32 v[12:13], 0
	v_mov_b64_e32 v[14:15], 0
	v_mov_b64_e32 v[16:17], 0
	v_mov_b64_e32 v[18:19], 0
	v_mov_b64_e32 v[20:21], 0
	v_mov_b64_e32 v[22:23], 0
	v_mov_b64_e32 v[24:25], 0
	v_mov_b64_e32 v[26:27], 0
	v_mov_b64_e32 v[28:29], 0
	v_mov_b64_e32 v[30:31], 0
	v_mov_b64_e32 v[32:33], 0
	v_mov_b64_e32 v[34:35], 0
	v_mov_b64_e32 v[36:37], 0
	v_mov_b64_e32 v[38:39], 0
	v_mov_b64_e32 v[40:41], 0
	v_mov_b64_e32 v[42:43], 0
	v_mov_b64_e32 v[44:45], 0
	v_mov_b64_e32 v[46:47], 0
	v_mov_b64_e32 v[48:49], 0
	v_mov_b64_e32 v[50:51], 0
	v_mov_b64_e32 v[52:53], 0
	v_mov_b64_e32 v[54:55], 0
	v_mov_b64_e32 v[56:57], 0
	v_mov_b64_e32 v[58:59], 0
	v_mov_b64_e32 v[60:61], 0
	v_mov_b64_e32 v[62:63], 0
	v_mov_b64_e32 v[64:65], 0
	v_mov_b64_e32 v[66:67], 0
	v_mov_b64_e32 v[68:69], 0
	v_mov_b64_e32 v[70:71], 0
	v_mov_b64_e32 v[72:73], 0
	v_mov_b64_e32 v[74:75], 0
	v_mov_b64_e32 v[76:77], 0
	v_mov_b64_e32 v[78:79], 0
	v_mov_b64_e32 v[80:81], 0
	v_mov_b64_e32 v[82:83], 0
	v_mov_b64_e32 v[84:85], 0
	v_mov_b64_e32 v[86:87], 0
	v_mov_b64_e32 v[88:89], 0
	v_mov_b64_e32 v[90:91], 0
	v_mov_b64_e32 v[92:93], 0
	v_mov_b64_e32 v[94:95], 0
	v_mov_b64_e32 v[96:97], 0
	v_mov_b64_e32 v[98:99], 0
	v_mov_b64_e32 v[100:101], 0
	v_mov_b64_e32 v[102:103], 0
	v_mov_b64_e32 v[104:105], 0
	v_mov_b64_e32 v[106:107], 0
	v_mov_b64_e32 v[108:109], 0
	v_mov_b64_e32 v[110:111], 0
	v_mov_b64_e32 v[112:113], 0
	v_mov_b64_e32 v[114:115], 0
	v_mov_b64_e32 v[116:117], 0
	v_mov_b64_e32 v[118:119], 0
	v_mov_b64_e32 v[120:121], 0
	v_mov_b64_e32 v[122:123], 0
	v_mov_b64_e32 v[124:125], 0
	v_mov_b64_e32 v[126:127], 0
	s_barrier
	s_barrier
	.p2align	6

; #define WAIT_V(n) asm volatile("s_waitcnt vmcnt(" #n ")" ::: "memory")
; #define BAR __builtin_amdgcn_s_barrier()
; template <int EPI>
; __device__ __forceinline__ void gemm_phase(const u16* __restrict__ A, const u16* __restrict__ Bt, const int K,
;                                            const int nN, char* shm, const EpiArgs& ea) {
;     ...
;     WAIT_V(0);
;     if (wr == 1) BAR;
;     BAR;
;     BAR;
;     for (int t = 0; t < nt - 2; t += 2) {
.LBB0_230:
	s_add_i32 s26, s69, 0x80
	s_lshr_b32 s70, s26, 7
	s_add_i32 s26, s33, 0x80
	s_lshr_b32 s73, s33, 7
	s_lshr_b32 s72, s69, 7
	s_lshr_b32 s71, s26, 7
	s_mul_i32 s71, s71, 0x164000
	s_mul_i32 s72, s72, 0x164000
	s_mul_i32 s73, s73, 0x164000
	s_mul_i32 s70, s70, 0x164000
	s_mov_b32 s74, -2
	s_mov_b32 s75, 0
	s_waitcnt vmcnt(0)
	v_mov_b64_e32 v[0:1], 0
	v_mov_b64_e32 v[2:3], 0
	v_mov_b64_e32 v[4:5], 0
	v_mov_b64_e32 v[6:7], 0
	v_mov_b64_e32 v[8:9], 0
	v_mov_b64_e32 v[10:11], 0
	v_mov_b64_e32 v[12:13], 0
	v_mov_b64_e32 v[14:15], 0
	v_mov_b64_e32 v[16:17], 0
	v_mov_b64_e32 v[18:19], 0
	v_mov_b64_e32 v[20:21], 0
	v_mov_b64_e32 v[22:23], 0
	v_mov_b64_e32 v[24:25], 0
	v_mov_b64_e32 v[26:27], 0
	v_mov_b64_e32 v[28:29], 0
	v_mov_b64_e32 v[30:31], 0
	v_mov_b64_e32 v[32:33], 0
	v_mov_b64_e32 v[34:35], 0
	v_mov_b64_e32 v[36:37], 0
	v_mov_b64_e32 v[38:39], 0
	v_mov_b64_e32 v[40:41], 0
	v_mov_b64_e32 v[42:43], 0
	v_mov_b64_e32 v[44:45], 0
	v_mov_b64_e32 v[46:47], 0
	v_mov_b64_e32 v[48:49], 0
	v_mov_b64_e32 v[50:51], 0
	v_mov_b64_e32 v[52:53], 0
	v_mov_b64_e32 v[54:55], 0
	v_mov_b64_e32 v[56:57], 0
	v_mov_b64_e32 v[58:59], 0
	v_mov_b64_e32 v[60:61], 0
	v_mov_b64_e32 v[62:63], 0
	v_mov_b64_e32 v[64:65], 0
	v_mov_b64_e32 v[66:67], 0
	v_mov_b64_e32 v[68:69], 0
	v_mov_b64_e32 v[70:71], 0
	v_mov_b64_e32 v[72:73], 0
	v_mov_b64_e32 v[74:75], 0
	v_mov_b64_e32 v[76:77], 0
	v_mov_b64_e32 v[78:79], 0
	v_mov_b64_e32 v[80:81], 0
	v_mov_b64_e32 v[82:83], 0
	v_mov_b64_e32 v[84:85], 0
	v_mov_b64_e32 v[86:87], 0
	v_mov_b64_e32 v[88:89], 0
	v_mov_b64_e32 v[90:91], 0
	v_mov_b64_e32 v[92:93], 0
	v_mov_b64_e32 v[94:95], 0
	v_mov_b64_e32 v[96:97], 0
	v_mov_b64_e32 v[98:99], 0
	v_mov_b64_e32 v[100:101], 0
	v_mov_b64_e32 v[102:103], 0
	v_mov_b64_e32 v[104:105], 0
	v_mov_b64_e32 v[106:107], 0
	v_mov_b64_e32 v[108:109], 0
	v_mov_b64_e32 v[110:111], 0
	v_mov_b64_e32 v[112:113], 0
	v_mov_b64_e32 v[114:115], 0
	v_mov_b64_e32 v[116:117], 0
	v_mov_b64_e32 v[118:119], 0
	v_mov_b64_e32 v[120:121], 0
	v_mov_b64_e32 v[122:123], 0
	v_mov_b64_e32 v[124:125], 0
	v_mov_b64_e32 v[126:127], 0
	s_barrier
	s_barrier
	.p2align	6

; #define WAIT_V(n) asm volatile("s_waitcnt vmcnt(" #n ")" ::: "memory")
; #define BAR __builtin_amdgcn_s_barrier()
; template <int EPI>
; __device__ __forceinline__ void gemm_phase(const u16* __restrict__ A, const u16* __restrict__ Bt, const int K,
;                                            const int nN, char* shm, const EpiArgs& ea) {
;     ...
;     WAIT_V(0);
;     if (wr == 1) BAR;
;     BAR;
;     BAR;
;     for (int t = 0; t < nt - 2; t += 2) {
.LBB0_305:
	s_add_i32 s26, s33, 0x80
	s_lshr_b32 s72, s26, 7
	s_add_i32 s26, s42, 0x80
	s_lshr_b32 s74, s42, 7
	s_lshr_b32 s73, s33, 7
	s_lshr_b32 s43, s26, 7
	s_mul_i32 s43, s43, 0x84000
	s_mul_i32 s73, s73, 0x84000
	s_mul_i32 s74, s74, 0x84000
	s_mul_i32 s72, s72, 0x84000
	s_mov_b32 s75, -2
	s_mov_b32 s78, 0
	s_waitcnt vmcnt(0)
	v_mov_b64_e32 v[0:1], 0
	v_mov_b64_e32 v[2:3], 0
	v_mov_b64_e32 v[4:5], 0
	v_mov_b64_e32 v[6:7], 0
	v_mov_b64_e32 v[8:9], 0
	v_mov_b64_e32 v[10:11], 0
	v_mov_b64_e32 v[12:13], 0
	v_mov_b64_e32 v[14:15], 0
	v_mov_b64_e32 v[16:17], 0
	v_mov_b64_e32 v[18:19], 0
	v_mov_b64_e32 v[20:21], 0
	v_mov_b64_e32 v[22:23], 0
	v_mov_b64_e32 v[24:25], 0
	v_mov_b64_e32 v[26:27], 0
	v_mov_b64_e32 v[28:29], 0
	v_mov_b64_e32 v[30:31], 0
	v_mov_b64_e32 v[32:33], 0
	v_mov_b64_e32 v[34:35], 0
	v_mov_b64_e32 v[36:37], 0
	v_mov_b64_e32 v[38:39], 0
	v_mov_b64_e32 v[40:41], 0
	v_mov_b64_e32 v[42:43], 0
	v_mov_b64_e32 v[44:45], 0
	v_mov_b64_e32 v[46:47], 0
	v_mov_b64_e32 v[48:49], 0
	v_mov_b64_e32 v[50:51], 0
	v_mov_b64_e32 v[52:53], 0
	v_mov_b64_e32 v[54:55], 0
	v_mov_b64_e32 v[56:57], 0
	v_mov_b64_e32 v[58:59], 0
	v_mov_b64_e32 v[60:61], 0
	v_mov_b64_e32 v[62:63], 0
	v_mov_b64_e32 v[64:65], 0
	v_mov_b64_e32 v[66:67], 0
	v_mov_b64_e32 v[68:69], 0
	v_mov_b64_e32 v[70:71], 0
	v_mov_b64_e32 v[72:73], 0
	v_mov_b64_e32 v[74:75], 0
	v_mov_b64_e32 v[76:77], 0
	v_mov_b64_e32 v[78:79], 0
	v_mov_b64_e32 v[80:81], 0
	v_mov_b64_e32 v[82:83], 0
	v_mov_b64_e32 v[84:85], 0
	v_mov_b64_e32 v[86:87], 0
	v_mov_b64_e32 v[88:89], 0
	v_mov_b64_e32 v[90:91], 0
	v_mov_b64_e32 v[92:93], 0
	v_mov_b64_e32 v[94:95], 0
	v_mov_b64_e32 v[96:97], 0
	v_mov_b64_e32 v[98:99], 0
	v_mov_b64_e32 v[100:101], 0
	v_mov_b64_e32 v[102:103], 0
	v_mov_b64_e32 v[104:105], 0
	v_mov_b64_e32 v[106:107], 0
	v_mov_b64_e32 v[108:109], 0
	v_mov_b64_e32 v[110:111], 0
	v_mov_b64_e32 v[112:113], 0
	v_mov_b64_e32 v[114:115], 0
	v_mov_b64_e32 v[116:117], 0
	v_mov_b64_e32 v[118:119], 0
	v_mov_b64_e32 v[120:121], 0
	v_mov_b64_e32 v[122:123], 0
	v_mov_b64_e32 v[124:125], 0
	v_mov_b64_e32 v[126:127], 0
	s_barrier
	s_barrier
	.p2align	6

; #define WAIT_V(n) asm volatile("s_waitcnt vmcnt(" #n ")" ::: "memory")
; #define BAR __builtin_amdgcn_s_barrier()
; template <int EPI>
; __device__ __forceinline__ void gemm_phase(const u16* __restrict__ A, const u16* __restrict__ Bt, const int K,
;                                            const int nN, char* shm, const EpiArgs& ea) {
;     ...
;     WAIT_V(0);
;     if (wr == 1) BAR;
;     BAR;
;     BAR;
;     for (int t = 0; t < nt - 2; t += 2) {
.LBB0_491:
	s_add_i32 s10, s58, 0x80
	s_lshr_b32 s59, s10, 7
	s_add_i32 s10, s33, 0x80
	s_lshr_b32 s62, s33, 7
	s_lshr_b32 s61, s58, 7
	s_lshr_b32 s60, s10, 7
	s_mul_i32 s60, s60, 0x84000
	s_mul_i32 s61, s61, 0x84000
	s_mul_i32 s62, s62, 0x84000
	s_mul_i32 s59, s59, 0x84000
	s_mov_b32 s63, -2
	s_mov_b32 s64, 0
	s_waitcnt vmcnt(0)
	v_mov_b64_e32 v[0:1], 0
	v_mov_b64_e32 v[2:3], 0
	v_mov_b64_e32 v[4:5], 0
	v_mov_b64_e32 v[6:7], 0
	v_mov_b64_e32 v[8:9], 0
	v_mov_b64_e32 v[10:11], 0
	v_mov_b64_e32 v[12:13], 0
	v_mov_b64_e32 v[14:15], 0
	v_mov_b64_e32 v[16:17], 0
	v_mov_b64_e32 v[18:19], 0
	v_mov_b64_e32 v[20:21], 0
	v_mov_b64_e32 v[22:23], 0
	v_mov_b64_e32 v[24:25], 0
	v_mov_b64_e32 v[26:27], 0
	v_mov_b64_e32 v[28:29], 0
	v_mov_b64_e32 v[30:31], 0
	v_mov_b64_e32 v[32:33], 0
	v_mov_b64_e32 v[34:35], 0
	v_mov_b64_e32 v[36:37], 0
	v_mov_b64_e32 v[38:39], 0
	v_mov_b64_e32 v[40:41], 0
	v_mov_b64_e32 v[42:43], 0
	v_mov_b64_e32 v[44:45], 0
	v_mov_b64_e32 v[46:47], 0
	v_mov_b64_e32 v[48:49], 0
	v_mov_b64_e32 v[50:51], 0
	v_mov_b64_e32 v[52:53], 0
	v_mov_b64_e32 v[54:55], 0
	v_mov_b64_e32 v[56:57], 0
	v_mov_b64_e32 v[58:59], 0
	v_mov_b64_e32 v[60:61], 0
	v_mov_b64_e32 v[62:63], 0
	v_mov_b64_e32 v[64:65], 0
	v_mov_b64_e32 v[66:67], 0
	v_mov_b64_e32 v[68:69], 0
	v_mov_b64_e32 v[70:71], 0
	v_mov_b64_e32 v[72:73], 0
	v_mov_b64_e32 v[74:75], 0
	v_mov_b64_e32 v[76:77], 0
	v_mov_b64_e32 v[78:79], 0
	v_mov_b64_e32 v[80:81], 0
	v_mov_b64_e32 v[82:83], 0
	v_mov_b64_e32 v[84:85], 0
	v_mov_b64_e32 v[86:87], 0
	v_mov_b64_e32 v[88:89], 0
	v_mov_b64_e32 v[90:91], 0
	v_mov_b64_e32 v[92:93], 0
	v_mov_b64_e32 v[94:95], 0
	v_mov_b64_e32 v[96:97], 0
	v_mov_b64_e32 v[98:99], 0
	v_mov_b64_e32 v[100:101], 0
	v_mov_b64_e32 v[102:103], 0
	v_mov_b64_e32 v[104:105], 0
	v_mov_b64_e32 v[106:107], 0
	v_mov_b64_e32 v[108:109], 0
	v_mov_b64_e32 v[110:111], 0
	v_mov_b64_e32 v[112:113], 0
	v_mov_b64_e32 v[114:115], 0
	v_mov_b64_e32 v[116:117], 0
	v_mov_b64_e32 v[118:119], 0
	v_mov_b64_e32 v[120:121], 0
	v_mov_b64_e32 v[122:123], 0
	v_mov_b64_e32 v[124:125], 0
	v_mov_b64_e32 v[126:127], 0
	s_barrier
	s_barrier
	.p2align	6

; #define WAIT_V(n) asm volatile("s_waitcnt vmcnt(" #n ")" ::: "memory")
; #define BAR __builtin_amdgcn_s_barrier()
; template <int EPI>
; __device__ __forceinline__ void gemm_phase(const u16* __restrict__ A, const u16* __restrict__ Bt, const int K,
;                                            const int nN, char* shm, const EpiArgs& ea) {
;     ...
;     WAIT_V(0);
;     if (wr == 1) BAR;
;     BAR;
;     BAR;
;     for (int t = 0; t < nt - 2; t += 2) {
.LBB0_564:
	s_add_i32 s6, s56, 0x80
	s_lshr_b32 s58, s6, 7
	s_add_i32 s6, s57, 0x80
	s_lshr_b32 s61, s57, 7
	s_lshr_b32 s60, s56, 7
	s_lshr_b32 s59, s6, 7
	s_mul_i32 s59, s59, 0x84000
	s_mul_i32 s60, s60, 0x84000
	s_mul_i32 s61, s61, 0x84000
	s_mul_i32 s58, s58, 0x84000
	s_mov_b32 s62, -2
	s_mov_b32 s63, 0
	s_waitcnt vmcnt(14)
	v_mov_b64_e32 v[0:1], 0
	v_mov_b64_e32 v[2:3], 0
	v_mov_b64_e32 v[4:5], 0
	v_mov_b64_e32 v[6:7], 0
	v_mov_b64_e32 v[8:9], 0
	v_mov_b64_e32 v[10:11], 0
	v_mov_b64_e32 v[12:13], 0
	v_mov_b64_e32 v[14:15], 0
	v_mov_b64_e32 v[16:17], 0
	v_mov_b64_e32 v[18:19], 0
	v_mov_b64_e32 v[20:21], 0
	v_mov_b64_e32 v[22:23], 0
	v_mov_b64_e32 v[24:25], 0
	v_mov_b64_e32 v[26:27], 0
	v_mov_b64_e32 v[28:29], 0
	v_mov_b64_e32 v[30:31], 0
	v_mov_b64_e32 v[32:33], 0
	v_mov_b64_e32 v[34:35], 0
	v_mov_b64_e32 v[36:37], 0
	v_mov_b64_e32 v[38:39], 0
	v_mov_b64_e32 v[40:41], 0
	v_mov_b64_e32 v[42:43], 0
	v_mov_b64_e32 v[44:45], 0
	v_mov_b64_e32 v[46:47], 0
	v_mov_b64_e32 v[48:49], 0
	v_mov_b64_e32 v[50:51], 0
	v_mov_b64_e32 v[52:53], 0
	v_mov_b64_e32 v[54:55], 0
	v_mov_b64_e32 v[56:57], 0
	v_mov_b64_e32 v[58:59], 0
	v_mov_b64_e32 v[60:61], 0
	v_mov_b64_e32 v[62:63], 0
	v_mov_b64_e32 v[64:65], 0
	v_mov_b64_e32 v[66:67], 0
	v_mov_b64_e32 v[68:69], 0
	v_mov_b64_e32 v[70:71], 0
	v_mov_b64_e32 v[72:73], 0
	v_mov_b64_e32 v[74:75], 0
	v_mov_b64_e32 v[76:77], 0
	v_mov_b64_e32 v[78:79], 0
	v_mov_b64_e32 v[80:81], 0
	v_mov_b64_e32 v[82:83], 0
	v_mov_b64_e32 v[84:85], 0
	v_mov_b64_e32 v[86:87], 0
	v_mov_b64_e32 v[88:89], 0
	v_mov_b64_e32 v[90:91], 0
	v_mov_b64_e32 v[92:93], 0
	v_mov_b64_e32 v[94:95], 0
	v_mov_b64_e32 v[96:97], 0
	v_mov_b64_e32 v[98:99], 0
	v_mov_b64_e32 v[100:101], 0
	v_mov_b64_e32 v[102:103], 0
	v_mov_b64_e32 v[104:105], 0
	v_mov_b64_e32 v[106:107], 0
	v_mov_b64_e32 v[108:109], 0
	v_mov_b64_e32 v[110:111], 0
	v_mov_b64_e32 v[112:113], 0
	v_mov_b64_e32 v[114:115], 0
	v_mov_b64_e32 v[116:117], 0
	v_mov_b64_e32 v[118:119], 0
	v_mov_b64_e32 v[120:121], 0
	v_mov_b64_e32 v[122:123], 0
	v_mov_b64_e32 v[124:125], 0
	v_mov_b64_e32 v[126:127], 0
	s_barrier
	s_barrier
	.p2align	6

; #define WAIT_V(n) asm volatile("s_waitcnt vmcnt(" #n ")" ::: "memory")
; #define BAR __builtin_amdgcn_s_barrier()
; template <int EPI>
; __device__ __forceinline__ void gemm_phase(const u16* __restrict__ A, const u16* __restrict__ Bt, const int K,
;                                            const int nN, char* shm, const EpiArgs& ea) {
;     ...
;     WAIT_V(0);
;     if (wr == 1) BAR;
;     BAR;
;     BAR;
;     for (int t = 0; t < nt - 2; t += 2) {
.LBB0_630:
	s_add_i32 s6, s33, 0x80
	s_lshr_b32 s48, s6, 7
	s_add_i32 s6, s47, 0x80
	s_lshr_b32 s51, s47, 7
	s_lshr_b32 s50, s33, 7
	s_lshr_b32 s49, s6, 7
	s_mul_i32 s49, s49, 0x164000
	s_mul_i32 s50, s50, 0x164000
	s_mul_i32 s51, s51, 0x164000
	s_mul_i32 s48, s48, 0x164000
	s_mov_b32 s52, -2
	s_mov_b32 s53, 0
	s_waitcnt vmcnt(14)
	v_mov_b64_e32 v[0:1], 0
	v_mov_b64_e32 v[2:3], 0
	v_mov_b64_e32 v[4:5], 0
	v_mov_b64_e32 v[6:7], 0
	v_mov_b64_e32 v[8:9], 0
	v_mov_b64_e32 v[10:11], 0
	v_mov_b64_e32 v[12:13], 0
	v_mov_b64_e32 v[14:15], 0
	v_mov_b64_e32 v[16:17], 0
	v_mov_b64_e32 v[18:19], 0
	v_mov_b64_e32 v[20:21], 0
	v_mov_b64_e32 v[22:23], 0
	v_mov_b64_e32 v[24:25], 0
	v_mov_b64_e32 v[26:27], 0
	v_mov_b64_e32 v[28:29], 0
	v_mov_b64_e32 v[30:31], 0
	v_mov_b64_e32 v[32:33], 0
	v_mov_b64_e32 v[34:35], 0
	v_mov_b64_e32 v[36:37], 0
	v_mov_b64_e32 v[38:39], 0
	v_mov_b64_e32 v[40:41], 0
	v_mov_b64_e32 v[42:43], 0
	v_mov_b64_e32 v[44:45], 0
	v_mov_b64_e32 v[46:47], 0
	v_mov_b64_e32 v[48:49], 0
	v_mov_b64_e32 v[50:51], 0
	v_mov_b64_e32 v[52:53], 0
	v_mov_b64_e32 v[54:55], 0
	v_mov_b64_e32 v[56:57], 0
	v_mov_b64_e32 v[58:59], 0
	v_mov_b64_e32 v[60:61], 0
	v_mov_b64_e32 v[62:63], 0
	v_mov_b64_e32 v[64:65], 0
	v_mov_b64_e32 v[66:67], 0
	v_mov_b64_e32 v[68:69], 0
	v_mov_b64_e32 v[70:71], 0
	v_mov_b64_e32 v[72:73], 0
	v_mov_b64_e32 v[74:75], 0
	v_mov_b64_e32 v[76:77], 0
	v_mov_b64_e32 v[78:79], 0
	v_mov_b64_e32 v[80:81], 0
	v_mov_b64_e32 v[82:83], 0
	v_mov_b64_e32 v[84:85], 0
	v_mov_b64_e32 v[86:87], 0
	v_mov_b64_e32 v[88:89], 0
	v_mov_b64_e32 v[90:91], 0
	v_mov_b64_e32 v[92:93], 0
	v_mov_b64_e32 v[94:95], 0
	v_mov_b64_e32 v[96:97], 0
	v_mov_b64_e32 v[98:99], 0
	v_mov_b64_e32 v[100:101], 0
	v_mov_b64_e32 v[102:103], 0
	v_mov_b64_e32 v[104:105], 0
	v_mov_b64_e32 v[106:107], 0
	v_mov_b64_e32 v[108:109], 0
	v_mov_b64_e32 v[110:111], 0
	v_mov_b64_e32 v[112:113], 0
	v_mov_b64_e32 v[114:115], 0
	v_mov_b64_e32 v[116:117], 0
	v_mov_b64_e32 v[118:119], 0
	v_mov_b64_e32 v[120:121], 0
	v_mov_b64_e32 v[122:123], 0
	v_mov_b64_e32 v[124:125], 0
	v_mov_b64_e32 v[126:127], 0
	s_barrier
	s_barrier
	.p2align	6
